# scan stage-C loads hoisted out of the unrolled loop (base for bisecting the sample-row GEMM edit)
# baseline (speedup 1.0000x reference)
.LBB0_1169:
	s_or_b64 exec, exec, s[48:49]
	v_readlane_b32 s0, v243, 31
	v_readlane_b32 s1, v243, 32
	v_readlane_b32 s2, v244, 24
	s_mov_b32 s1, s2
	s_waitcnt lgkmcnt(5)
	v_pk_mul_f32 v[62:63], v[88:89], s[0:1]
	v_readlane_b32 s0, v243, 40
	v_readlane_b32 s1, v243, 41
	v_pk_mul_f32 v[64:65], v[92:93], s[36:37]
	v_lshlrev_b32_e32 v79, 16, v133
	s_waitcnt lgkmcnt(2)
	v_pk_mul_f32 v[66:67], v[96:97], s[0:1]
	v_readlane_b32 s0, v243, 51
	v_readlane_b32 s1, v243, 52
	v_mov_b32_e32 v78, v109
	v_pk_mul_f32 v[62:63], v[78:79], v[62:63] op_sel_hi:[0,1]
	v_pk_mul_f32 v[68:69], v[98:99], s[0:1]
	v_readlane_b32 s0, v242, 0
	v_readlane_b32 s1, v242, 1
	v_pk_mul_f32 v[64:65], v[78:79], v[64:65] op_sel_hi:[0,1]
	v_cvt_pk_bf16_f32 v62, v62, v63
	v_pk_mul_f32 v[70:71], v[106:107], s[0:1]
	s_mov_b32 s0, s79
	s_mov_b32 s1, s78
	v_cvt_pk_bf16_f32 v63, v64, v65
	v_pk_mul_f32 v[64:65], v[78:79], v[66:67] op_sel_hi:[0,1]
	v_pk_mul_f32 v[66:67], v[78:79], v[68:69] op_sel_hi:[0,1]
	v_pk_mul_f32 v[72:73], v[112:113], s[0:1]
	v_cvt_pk_bf16_f32 v64, v64, v65
	v_cvt_pk_bf16_f32 v65, v66, v67
	v_pk_mul_f32 v[74:75], v[116:117], s[6:7]
	v_pk_mul_f32 v[76:77], v[140:141], s[18:19]
	ds_write_b128 v188, v[62:65] offset:4096
	v_pk_mul_f32 v[62:63], v[78:79], v[70:71] op_sel_hi:[0,1]
	v_pk_mul_f32 v[64:65], v[78:79], v[72:73] op_sel_hi:[0,1]
	v_cvt_pk_bf16_f32 v62, v62, v63
	v_cvt_pk_bf16_f32 v63, v64, v65
	v_pk_mul_f32 v[64:65], v[78:79], v[74:75] op_sel_hi:[0,1]
	v_pk_mul_f32 v[66:67], v[78:79], v[76:77] op_sel_hi:[0,1]
	v_cvt_pk_bf16_f32 v64, v64, v65
	v_cvt_pk_bf16_f32 v65, v66, v67
	v_pk_mul_f32 v[2:3], v[2:3], v[78:79] op_sel_hi:[1,0]
	ds_write_b128 v188, v[62:65] offset:4112
	v_cvt_pk_bf16_f32 v62, v2, v3
	v_pk_mul_f32 v[2:3], v[86:87], v[78:79] op_sel_hi:[1,0]
	v_lshlrev_b32_e32 v5, 16, v5
	v_cvt_pk_bf16_f32 v63, v2, v3
	v_pk_mul_f32 v[2:3], v[90:91], v[78:79] op_sel_hi:[1,0]
	v_lshlrev_b32_e32 v80, 16, v191
	v_cvt_pk_bf16_f32 v64, v2, v3
	v_pk_mul_f32 v[2:3], v[94:95], v[78:79] op_sel_hi:[1,0]
	v_lshlrev_b32_e32 v81, 16, v192
	v_cvt_pk_bf16_f32 v65, v2, v3
	v_pk_mul_f32 v[2:3], v[102:103], v[78:79] op_sel_hi:[1,0]
	ds_write_b128 v188, v[62:65] offset:6144
	v_cvt_pk_bf16_f32 v62, v2, v3
	v_pk_mul_f32 v[2:3], v[104:105], v[78:79] op_sel_hi:[1,0]
	v_lshlrev_b32_e32 v82, 16, v193
	v_cvt_pk_bf16_f32 v63, v2, v3
	v_pk_mul_f32 v[2:3], v[110:111], v[78:79] op_sel_hi:[1,0]
	v_lshlrev_b32_e32 v83, 16, v194
	v_cvt_pk_bf16_f32 v64, v2, v3
	v_pk_mul_f32 v[2:3], v[114:115], v[78:79] op_sel_hi:[1,0]
	v_lshlrev_b32_e32 v84, 16, v195
	v_lshlrev_b32_e32 v85, 16, v196
	v_cvt_pk_bf16_f32 v65, v2, v3
	v_lshlrev_b32_e32 v88, 16, v197
	v_lshlrev_b32_e32 v89, 16, v198
	v_lshlrev_b32_e32 v92, 16, v199
	v_lshlrev_b32_e32 v93, 16, v200
	v_lshlrev_b32_e32 v96, 16, v201
	v_lshlrev_b32_e32 v97, 16, v202
	v_lshlrev_b32_e32 v98, 16, v203
	v_lshlrev_b32_e32 v99, 16, v204
	ds_write_b128 v188, v[62:65] offset:6160
	v_cvt_pk_bf16_f32 v62, v5, v79
	v_cvt_pk_bf16_f32 v63, v80, v81
	v_cvt_pk_bf16_f32 v64, v82, v83
	v_cvt_pk_bf16_f32 v65, v84, v85
	ds_write_b128 v188, v[62:65] offset:10752
	v_cvt_pk_bf16_f32 v62, v88, v89
	v_cvt_pk_bf16_f32 v63, v92, v93
	v_cvt_pk_bf16_f32 v64, v96, v97
	v_cvt_pk_bf16_f32 v65, v98, v99
	v_readlane_b32 s3, v244, 25
	ds_write_b128 v188, v[62:65] offset:10768
	ds_write_b32 v183, v109 offset:12864
	s_waitcnt lgkmcnt(0)
	s_barrier
	v_readlane_b32 s2, v243, 5
	v_readlane_b32 s3, v243, 6
	s_mov_b64 s[0:1], -1
	s_and_b64 vcc, exec, s[2:3]
	s_cbranch_vccz .LBB0_1174
	v_readlane_b32 s0, v243, 30
	v_readlane_b32 s2, v244, 38
	v_readlane_b32 s4, v244, 44
	v_readlane_b32 s6, v244, 52
	s_cmp_eq_u32 s0, 0
	v_readlane_b32 s3, v244, 39
	v_readlane_b32 s5, v244, 45
	v_readlane_b32 s7, v244, 53
	s_mov_b32 s1, 0xffff0000
	s_cbranch_scc1 .LBB0_1173
	v_readlane_b32 s0, v243, 28
	ds_read_b128 v[62:65], v160 offset:256
	ds_read_b128 v[66:69], v160
	ds_read_b128 v[70:73], v160 offset:16
	ds_read_b128 v[74:77], v160 offset:272
	s_lshl_b32 s0, s0, 2
	s_and_b32 s0, s0, 0x200
	v_add_u32_e32 v5, s0, v169
	v_ashrrev_i32_e32 v133, 31, v132
	v_readlane_b32 s0, v243, 29
	v_lshlrev_b64 v[2:3], 12, v[132:133]
	s_and_b32 s0, s0, 0x4000
	v_lshl_add_u64 v[2:3], v[136:137], 0, v[2:3]
	v_add_u32_e32 v83, s0, v171
	s_waitcnt lgkmcnt(3)
	v_mov_b32_e32 v78, v63
	v_mov_b32_e32 v79, v65
	s_waitcnt lgkmcnt(2)
	v_mov_b32_e32 v80, v67
	v_mov_b32_e32 v81, v69
	v_mov_b32_e32 v63, v64
	v_mov_b32_e32 v67, v68
	s_waitcnt lgkmcnt(0)
	v_mov_b32_e32 v64, v75
	v_mov_b32_e32 v65, v77
	v_mov_b32_e32 v68, v71
	v_mov_b32_e32 v69, v73
	v_mov_b32_e32 v75, v76
	v_mov_b32_e32 v71, v72
	s_mov_b64 s[68:69], 0
	v_mov_b32_e32 v72, v190
	s_mov_b32 s34, 0x38100000
	s_mov_b32 s35, 0
	v_lshl_add_u64 v[224:225], v[2:3], 0, s[34:35]
	global_load_dwordx4 v[192:195], v[224:225], off
	s_mov_b32 s34, 0x34000000
	v_lshl_add_u64 v[226:227], v[2:3], 0, s[34:35]
	global_load_dwordx4 v[196:199], v[226:227], off
	v_add_u32_e32 v228, 0, v72
	v_ashrrev_i32_e32 v229, 31, v228
	v_lshlrev_b64 v[228:229], 12, v[228:229]
	v_lshl_or_b32 v228, v124, 1, v228
	v_lshl_add_u64 v[230:231], s[4:5], 0, v[228:229]
	global_load_dwordx4 v[200:203], v[230:231], off
	v_lshl_add_u64 v[232:233], s[2:3], 0, v[228:229]
	global_load_dwordx4 v[204:207], v[232:233], off
	s_mov_b32 s34, 0x38140000
	s_mov_b32 s35, 0
	v_lshl_add_u64 v[224:225], v[2:3], 0, s[34:35]
	global_load_dwordx4 v[208:211], v[224:225], off
	s_mov_b32 s34, 0x34040000
	v_lshl_add_u64 v[226:227], v[2:3], 0, s[34:35]
	global_load_dwordx4 v[212:215], v[226:227], off
	v_add_u32_e32 v228, 64, v72
	v_ashrrev_i32_e32 v229, 31, v228
	v_lshlrev_b64 v[228:229], 12, v[228:229]
	v_lshl_or_b32 v228, v124, 1, v228
	v_lshl_add_u64 v[230:231], s[4:5], 0, v[228:229]
	global_load_dwordx4 v[216:219], v[230:231], off
	v_lshl_add_u64 v[232:233], s[2:3], 0, v[228:229]
	global_load_dwordx4 v[220:223], v[232:233], off
.LBB0_1172:
	v_lshl_add_u64 v[76:77], v[2:3], 0, s[68:69]
	v_add_u32_e32 v85, 0, v5
	v_add_co_u32_e32 v84, vcc, 0x38100000, v76
	v_add_u32_e32 v82, 0, v83
	v_ashrrev_i32_e32 v73, 31, v72
	v_add_u32_e32 v99, 0x21e00, v85
	v_add_u32_e32 v106, 0x21e80, v85
	v_addc_co_u32_e32 v85, vcc, 0, v77, vcc
	s_mov_b32 s0, 0x1ba00000
	v_add_u32_e32 v86, 0x19c00, v82
	v_add_u32_e32 v91, 0x19e00, v82
	v_add_u32_e32 v95, 0x1a000, v82
	v_lshlrev_b64 v[88:89], 12, v[72:73]
	v_add_co_u32_e32 v90, vcc, 0x34000000, v76
	v_add_u32_e32 v87, 0x19d00, v82
	v_add_u32_e32 v94, 0x19f00, v82
	v_add_u32_e32 v96, 0x1a100, v82
	v_add_u32_e32 v97, 0x1a200, v82
	v_add_u32_e32 v98, 0x1a300, v82
	v_add_co_u32_e64 v92, s[34:35], s0, v76
	v_add_u32_e32 v73, 0x19c40, v82
	v_add_u32_e32 v100, 0x19d40, v82
	v_add_u32_e32 v101, 0x19e40, v82
	v_add_u32_e32 v102, 0x19f40, v82
	v_add_u32_e32 v103, 0x1a040, v82
	v_add_u32_e32 v104, 0x1a140, v82
	v_add_u32_e32 v105, 0x1a240, v82
	v_add_u32_e32 v82, 0x1a340, v82
	ds_read_u16 v107, v86
	ds_read_u16 v108, v91
	ds_read_u16 v109, v94
	ds_read_u16 v95, v95
	ds_read_u16 v110, v97
	ds_read_u16 v111, v98
	ds_read_u16 v112, v96
	ds_read_u16 v113, v87
	v_lshl_or_b32 v88, v124, 1, v88
	v_addc_co_u32_e32 v91, vcc, 0, v77, vcc
	v_addc_co_u32_e64 v93, s[34:35], 0, v77, s[34:35]
	ds_read_b32 v94, v99
	ds_read_u16 v73, v73
	ds_read_u16 v114, v101
	ds_read_u16 v115, v102
	ds_read_u16 v116, v103
	ds_read_u16 v117, v105
	ds_read_u16 v133, v104
	ds_read_u16 v140, v100
	ds_read_u16 v141, v82
	ds_read_b32 v82, v106
	s_waitcnt vmcnt(7)
	s_nop 1
	v_mov_b32_e32 v84, v192
	v_mov_b32_e32 v85, v193
	v_mov_b32_e32 v86, v194
	v_mov_b32_e32 v87, v195
	v_lshl_add_u64 v[96:97], s[2:3], 0, v[88:89]
	v_lshl_add_u64 v[98:99], s[4:5], 0, v[88:89]
	v_lshl_add_u64 v[76:77], s[6:7], 0, v[88:89]
	s_waitcnt vmcnt(6)
	s_nop 1
	v_mov_b32_e32 v88, v196
	v_mov_b32_e32 v89, v197
	v_mov_b32_e32 v90, v198
	v_mov_b32_e32 v91, v199
	s_waitcnt lgkmcnt(14)
	v_lshlrev_b32_e32 v100, 16, v107
	v_lshlrev_b32_e32 v101, 16, v108
	s_waitcnt lgkmcnt(10)
	v_lshlrev_b32_e32 v102, 16, v113
	s_waitcnt lgkmcnt(8)
	v_lshlrev_b32_e32 v108, 16, v73
	v_add_f32_e32 v73, 0, v100
	v_add_f32_e32 v73, v73, v102
	v_lshlrev_b32_e32 v103, 16, v109
	v_add_f32_e32 v73, v73, v101
	v_lshlrev_b32_e32 v104, 16, v95
	v_add_f32_e32 v73, v73, v103
	v_lshlrev_b32_e32 v106, 16, v112
	v_add_f32_e32 v73, v73, v104
	v_lshlrev_b32_e32 v105, 16, v110
	v_add_f32_e32 v73, v73, v106
	v_lshlrev_b32_e32 v107, 16, v111
	v_add_f32_e32 v73, v73, v105
	v_add_f32_e32 v73, v73, v107
	s_waitcnt lgkmcnt(5)
	v_lshlrev_b32_e32 v112, 16, v116
	s_waitcnt lgkmcnt(4)
	v_lshlrev_b32_e32 v113, 16, v117
	v_add_f32_dpp v73, v73, v73 quad_perm:[1,0,3,2] row_mask:0xf bank_mask:0xf bound_ctrl:1
	s_waitcnt lgkmcnt(2)
	v_lshlrev_b32_e32 v110, 16, v140
	v_add_f32_e32 v95, 0, v108
	v_add_f32_dpp v73, v73, v73 quad_perm:[2,3,0,1] row_mask:0xf bank_mask:0xf bound_ctrl:1
	v_lshlrev_b32_e32 v109, 16, v114
	v_add_f32_e32 v95, v95, v110
	v_add_f32_dpp v73, v73, v73 row_half_mirror row_mask:0xf bank_mask:0xf bound_ctrl:1
	v_mul_f32_e32 v116, 0x3c800000, v73
	v_pk_add_f32 v[100:101], v[100:101], v[116:117] op_sel_hi:[1,0] neg_lo:[0,1] neg_hi:[0,1]
	v_pk_add_f32 v[102:103], v[102:103], v[116:117] op_sel_hi:[1,0] neg_lo:[0,1] neg_hi:[0,1]
	v_pk_add_f32 v[104:105], v[104:105], v[116:117] op_sel_hi:[1,0] neg_lo:[0,1] neg_hi:[0,1]
	v_pk_add_f32 v[106:107], v[106:107], v[116:117] op_sel_hi:[1,0] neg_lo:[0,1] neg_hi:[0,1]
	v_mov_b32_e32 v116, v103
	v_mov_b32_e32 v117, v101
	v_mul_f32_e32 v73, v100, v100
	v_pk_mul_f32 v[116:117], v[116:117], v[116:117]
	v_fmac_f32_e32 v73, v102, v102
	v_mov_b32_e32 v142, v106
	v_mov_b32_e32 v143, v104
	v_add_f32_e32 v73, v117, v73
	v_pk_mul_f32 v[142:143], v[142:143], v[142:143]
	v_add_f32_e32 v73, v116, v73
	v_mov_b32_e32 v144, v107
	v_mov_b32_e32 v145, v105
	v_add_f32_e32 v73, v143, v73
	v_pk_mul_f32 v[144:145], v[144:145], v[144:145]
	v_add_f32_e32 v73, v142, v73
	v_add_f32_e32 v73, v145, v73
	v_add_f32_e32 v73, v144, v73
	v_lshlrev_b32_e32 v111, 16, v115
	v_add_f32_e32 v95, v95, v109
	v_add_f32_dpp v73, v73, v73 quad_perm:[1,0,3,2] row_mask:0xf bank_mask:0xf bound_ctrl:1
	v_add_f32_e32 v95, v95, v111
	v_lshlrev_b32_e32 v114, 16, v133
	v_add_f32_dpp v73, v73, v73 quad_perm:[2,3,0,1] row_mask:0xf bank_mask:0xf bound_ctrl:1
	v_add_f32_e32 v95, v95, v112
	v_add_f32_e32 v95, v95, v114
	v_add_f32_dpp v73, v73, v73 row_half_mirror row_mask:0xf bank_mask:0xf bound_ctrl:1
	v_fmamk_f32 v73, v73, 0x3c800000, v184
	v_rsq_f32_e32 v116, v73
	s_waitcnt lgkmcnt(1)
	v_lshlrev_b32_e32 v115, 16, v141
	v_add_f32_e32 v95, v95, v113
	v_add_f32_e32 v95, v95, v115
	v_pk_mul_f32 v[100:101], v[100:101], v[116:117] op_sel_hi:[1,0]
	v_pk_mul_f32 v[102:103], v[102:103], v[116:117] op_sel_hi:[1,0]
	v_add_f32_dpp v95, v95, v95 quad_perm:[1,0,3,2] row_mask:0xf bank_mask:0xf bound_ctrl:1
	v_pk_mul_f32 v[104:105], v[104:105], v[116:117] op_sel_hi:[1,0]
	v_pk_mul_f32 v[106:107], v[106:107], v[116:117] op_sel_hi:[1,0]
	v_add_f32_dpp v95, v95, v95 quad_perm:[2,3,0,1] row_mask:0xf bank_mask:0xf bound_ctrl:1
	v_pk_fma_f32 v[100:101], v[66:67], v[100:101], v[62:63]
	v_pk_fma_f32 v[102:103], v[80:81], v[102:103], v[78:79]
	v_add_f32_dpp v95, v95, v95 row_half_mirror row_mask:0xf bank_mask:0xf bound_ctrl:1
	v_pk_fma_f32 v[104:105], v[70:71], v[104:105], v[74:75]
	v_pk_fma_f32 v[106:107], v[68:69], v[106:107], v[64:65]
	v_mul_f32_e32 v140, 0x3c800000, v95
	v_add_u32_e32 v83, 0x80, v83
	v_lshlrev_b32_e32 v117, 16, v85
	v_lshlrev_b32_e32 v116, 16, v84
	v_and_b32_e32 v85, 0xffff0000, v85
	v_and_b32_e32 v84, 0xffff0000, v84
	v_lshlrev_b32_e32 v145, 16, v89
	v_lshlrev_b32_e32 v144, 16, v88
	v_and_b32_e32 v89, 0xffff0000, v89
	v_and_b32_e32 v88, 0xffff0000, v88
	v_lshlrev_b32_e32 v147, 16, v91
	v_lshlrev_b32_e32 v146, 16, v90
	v_and_b32_e32 v91, 0xffff0000, v91
	v_and_b32_e32 v90, 0xffff0000, v90
	v_lshlrev_b32_e32 v143, 16, v87
	v_lshlrev_b32_e32 v142, 16, v86
	v_and_b32_e32 v87, 0xffff0000, v87
	v_and_b32_e32 v86, 0xffff0000, v86
	v_pk_fma_f32 v[100:101], v[94:95], v[144:145], v[100:101] op_sel_hi:[0,1,1]
	v_pk_fma_f32 v[88:89], v[94:95], v[88:89], v[102:103] op_sel_hi:[0,1,1]
	v_pk_fma_f32 v[102:103], v[94:95], v[146:147], v[104:105] op_sel_hi:[0,1,1]
	v_pk_fma_f32 v[90:91], v[94:95], v[90:91], v[106:107] op_sel_hi:[0,1,1]
	v_pk_mul_f32 v[94:95], v[100:101], v[116:117]
	v_pk_mul_f32 v[84:85], v[88:89], v[84:85]
	v_pk_mul_f32 v[88:89], v[102:103], v[142:143]
	v_pk_mul_f32 v[86:87], v[90:91], v[86:87]
	v_bfe_u32 v101, v94, 16, 1
	v_bfe_u32 v73, v87, 16, 1
	v_bfe_u32 v90, v86, 16, 1
	v_bfe_u32 v102, v95, 16, 1
	v_bfe_u32 v103, v88, 16, 1
	v_bfe_u32 v104, v89, 16, 1
	v_bfe_u32 v91, v85, 16, 1
	v_bfe_u32 v100, v84, 16, 1
	v_add3_u32 v86, v86, v90, s33
	v_add3_u32 v73, v87, v73, s33
	v_add3_u32 v87, v89, v104, s33
	v_add3_u32 v88, v88, v103, s33
	v_add3_u32 v89, v95, v102, s33
	v_add3_u32 v90, v94, v101, s33
	v_add3_u32 v84, v84, v100, s33
	v_add3_u32 v85, v85, v91, s33
	v_lshrrev_b32_e32 v90, 16, v90
	v_lshrrev_b32_e32 v89, 16, v89
	v_lshrrev_b32_e32 v88, 16, v88
	v_lshrrev_b32_e32 v87, 16, v87
	v_and_or_b32 v87, v73, s1, v87
	v_and_or_b32 v86, v86, s1, v88
	v_and_or_b32 v85, v85, s1, v89
	v_and_or_b32 v84, v84, s1, v90
	global_store_dwordx4 v[92:93], v[84:87], off
	s_waitcnt vmcnt(6)
	s_nop 1
	v_mov_b32_e32 v84, v200
	v_mov_b32_e32 v85, v201
	v_mov_b32_e32 v86, v202
	v_mov_b32_e32 v87, v203
	s_nop 0
	s_waitcnt vmcnt(5)
	s_nop 1
	v_mov_b32_e32 v88, v204
	v_mov_b32_e32 v89, v205
	v_mov_b32_e32 v90, v206
	v_mov_b32_e32 v91, v207
	v_pk_add_f32 v[92:93], v[108:109], v[140:141] op_sel_hi:[1,0] neg_lo:[0,1] neg_hi:[0,1]
	v_pk_add_f32 v[94:95], v[110:111], v[140:141] op_sel_hi:[1,0] neg_lo:[0,1] neg_hi:[0,1]
	v_mov_b32_e32 v101, v93
	v_mov_b32_e32 v100, v95
	v_mul_f32_e32 v73, v92, v92
	v_pk_add_f32 v[96:97], v[112:113], v[140:141] op_sel_hi:[1,0] neg_lo:[0,1] neg_hi:[0,1]
	v_pk_add_f32 v[98:99], v[114:115], v[140:141] op_sel_hi:[1,0] neg_lo:[0,1] neg_hi:[0,1]
	v_pk_mul_f32 v[100:101], v[100:101], v[100:101]
	v_fmac_f32_e32 v73, v94, v94
	v_mov_b32_e32 v102, v98
	v_mov_b32_e32 v103, v96
	v_add_f32_e32 v73, v101, v73
	v_pk_mul_f32 v[102:103], v[102:103], v[102:103]
	v_add_f32_e32 v73, v100, v73
	v_mov_b32_e32 v104, v99
	v_mov_b32_e32 v105, v97
	v_add_f32_e32 v73, v103, v73
	v_pk_mul_f32 v[104:105], v[104:105], v[104:105]
	v_add_f32_e32 v73, v102, v73
	v_add_f32_e32 v73, v105, v73
	v_add_f32_e32 v73, v104, v73
	s_add_u32 s68, s68, 0x40000
	s_addc_u32 s69, s69, 0
	v_add_f32_dpp v73, v73, v73 quad_perm:[1,0,3,2] row_mask:0xf bank_mask:0xf bound_ctrl:1
	v_add_u32_e32 v5, 0x100, v5
	v_add_u32_e32 v72, 64, v72
	v_add_f32_dpp v73, v73, v73 quad_perm:[2,3,0,1] row_mask:0xf bank_mask:0xf bound_ctrl:1
	s_cmp_lg_u32 s68, 0x80000
	v_lshlrev_b32_e32 v105, 16, v87
	v_add_f32_dpp v73, v73, v73 row_half_mirror row_mask:0xf bank_mask:0xf bound_ctrl:1
	v_fmamk_f32 v73, v73, 0x3c800000, v184
	v_rsq_f32_e32 v100, v73
	v_lshlrev_b32_e32 v104, 16, v86
	v_and_b32_e32 v87, 0xffff0000, v87
	v_and_b32_e32 v86, 0xffff0000, v86
	v_pk_mul_f32 v[92:93], v[92:93], v[100:101] op_sel_hi:[1,0]
	v_pk_mul_f32 v[94:95], v[94:95], v[100:101] op_sel_hi:[1,0]
	v_pk_mul_f32 v[96:97], v[96:97], v[100:101] op_sel_hi:[1,0]
	v_pk_mul_f32 v[98:99], v[98:99], v[100:101] op_sel_hi:[1,0]
	v_pk_fma_f32 v[92:93], v[66:67], v[92:93], v[62:63]
	v_pk_fma_f32 v[94:95], v[80:81], v[94:95], v[78:79]
	v_pk_fma_f32 v[96:97], v[70:71], v[96:97], v[74:75]
	v_pk_fma_f32 v[98:99], v[68:69], v[98:99], v[64:65]
	v_lshlrev_b32_e32 v101, 16, v85
	v_lshlrev_b32_e32 v100, 16, v84
	v_and_b32_e32 v85, 0xffff0000, v85
	v_and_b32_e32 v84, 0xffff0000, v84
	v_lshlrev_b32_e32 v103, 16, v89
	v_lshlrev_b32_e32 v102, 16, v88
	v_and_b32_e32 v89, 0xffff0000, v89
	v_and_b32_e32 v88, 0xffff0000, v88
	v_lshlrev_b32_e32 v107, 16, v91
	v_lshlrev_b32_e32 v106, 16, v90
	v_and_b32_e32 v91, 0xffff0000, v91
	v_and_b32_e32 v90, 0xffff0000, v90
	s_waitcnt lgkmcnt(0)
	v_pk_fma_f32 v[92:93], v[82:83], v[100:101], v[92:93] op_sel_hi:[0,1,1]
	v_pk_fma_f32 v[84:85], v[82:83], v[84:85], v[94:95] op_sel_hi:[0,1,1]
	v_pk_fma_f32 v[94:95], v[82:83], v[104:105], v[96:97] op_sel_hi:[0,1,1]
	v_pk_fma_f32 v[86:87], v[82:83], v[86:87], v[98:99] op_sel_hi:[0,1,1]
	v_pk_mul_f32 v[92:93], v[92:93], v[102:103]
	v_pk_mul_f32 v[84:85], v[84:85], v[88:89]
	v_pk_mul_f32 v[88:89], v[94:95], v[106:107]
	v_pk_mul_f32 v[86:87], v[86:87], v[90:91]
	v_bfe_u32 v94, v92, 16, 1
	v_bfe_u32 v73, v87, 16, 1
	v_bfe_u32 v82, v86, 16, 1
	v_bfe_u32 v95, v93, 16, 1
	v_bfe_u32 v96, v88, 16, 1
	v_bfe_u32 v97, v89, 16, 1
	v_bfe_u32 v90, v85, 16, 1
	v_bfe_u32 v91, v84, 16, 1
	v_add3_u32 v82, v86, v82, s33
	v_add3_u32 v73, v87, v73, s33
	v_add3_u32 v86, v89, v97, s33
	v_add3_u32 v87, v88, v96, s33
	v_add3_u32 v88, v93, v95, s33
	v_add3_u32 v89, v92, v94, s33
	v_add3_u32 v84, v84, v91, s33
	v_add3_u32 v85, v85, v90, s33
	v_lshrrev_b32_e32 v89, 16, v89
	v_lshrrev_b32_e32 v88, 16, v88
	v_lshrrev_b32_e32 v90, 16, v87
	v_lshrrev_b32_e32 v86, 16, v86
	v_and_or_b32 v87, v73, s1, v86
	v_and_or_b32 v86, v82, s1, v90
	v_and_or_b32 v85, v85, s1, v88
	v_and_or_b32 v84, v84, s1, v89
	global_store_dwordx4 v[76:77], v[84:87], off
	s_nop 1
	v_lshl_add_u64 v[76:77], v[2:3], 0, s[68:69]
	v_add_u32_e32 v85, 0, v5
	v_add_co_u32_e32 v84, vcc, 0x38100000, v76
	v_add_u32_e32 v82, 0, v83
	v_ashrrev_i32_e32 v73, 31, v72
	v_add_u32_e32 v99, 0x21e00, v85
	v_add_u32_e32 v106, 0x21e80, v85
	v_addc_co_u32_e32 v85, vcc, 0, v77, vcc
	s_mov_b32 s0, 0x1ba00000
	v_add_u32_e32 v86, 0x19c00, v82
	v_add_u32_e32 v91, 0x19e00, v82
	v_add_u32_e32 v95, 0x1a000, v82
	v_lshlrev_b64 v[88:89], 12, v[72:73]
	v_add_co_u32_e32 v90, vcc, 0x34000000, v76
	v_add_u32_e32 v87, 0x19d00, v82
	v_add_u32_e32 v94, 0x19f00, v82
	v_add_u32_e32 v96, 0x1a100, v82
	v_add_u32_e32 v97, 0x1a200, v82
	v_add_u32_e32 v98, 0x1a300, v82
	v_add_co_u32_e64 v92, s[34:35], s0, v76
	v_add_u32_e32 v73, 0x19c40, v82
	v_add_u32_e32 v100, 0x19d40, v82
	v_add_u32_e32 v101, 0x19e40, v82
	v_add_u32_e32 v102, 0x19f40, v82
	v_add_u32_e32 v103, 0x1a040, v82
	v_add_u32_e32 v104, 0x1a140, v82
	v_add_u32_e32 v105, 0x1a240, v82
	v_add_u32_e32 v82, 0x1a340, v82
	ds_read_u16 v107, v86
	ds_read_u16 v108, v91
	ds_read_u16 v109, v94
	ds_read_u16 v95, v95
	ds_read_u16 v110, v97
	ds_read_u16 v111, v98
	ds_read_u16 v112, v96
	ds_read_u16 v113, v87
	v_lshl_or_b32 v88, v124, 1, v88
	v_addc_co_u32_e32 v91, vcc, 0, v77, vcc
	v_addc_co_u32_e64 v93, s[34:35], 0, v77, s[34:35]
	ds_read_b32 v94, v99
	ds_read_u16 v73, v73
	ds_read_u16 v114, v101
	ds_read_u16 v115, v102
	ds_read_u16 v116, v103
	ds_read_u16 v117, v105
	ds_read_u16 v133, v104
	ds_read_u16 v140, v100
	ds_read_u16 v141, v82
	ds_read_b32 v82, v106
	s_waitcnt vmcnt(5)
	s_nop 1
	v_mov_b32_e32 v84, v208
	v_mov_b32_e32 v85, v209
	v_mov_b32_e32 v86, v210
	v_mov_b32_e32 v87, v211
	v_lshl_add_u64 v[96:97], s[2:3], 0, v[88:89]
	v_lshl_add_u64 v[98:99], s[4:5], 0, v[88:89]
	v_lshl_add_u64 v[76:77], s[6:7], 0, v[88:89]
	s_waitcnt vmcnt(4)
	s_nop 1
	v_mov_b32_e32 v88, v212
	v_mov_b32_e32 v89, v213
	v_mov_b32_e32 v90, v214
	v_mov_b32_e32 v91, v215
	s_waitcnt lgkmcnt(14)
	v_lshlrev_b32_e32 v100, 16, v107
	v_lshlrev_b32_e32 v101, 16, v108
	s_waitcnt lgkmcnt(10)
	v_lshlrev_b32_e32 v102, 16, v113
	s_waitcnt lgkmcnt(8)
	v_lshlrev_b32_e32 v108, 16, v73
	v_add_f32_e32 v73, 0, v100
	v_add_f32_e32 v73, v73, v102
	v_lshlrev_b32_e32 v103, 16, v109
	v_add_f32_e32 v73, v73, v101
	v_lshlrev_b32_e32 v104, 16, v95
	v_add_f32_e32 v73, v73, v103
	v_lshlrev_b32_e32 v106, 16, v112
	v_add_f32_e32 v73, v73, v104
	v_lshlrev_b32_e32 v105, 16, v110
	v_add_f32_e32 v73, v73, v106
	v_lshlrev_b32_e32 v107, 16, v111
	v_add_f32_e32 v73, v73, v105
	v_add_f32_e32 v73, v73, v107
	s_waitcnt lgkmcnt(5)
	v_lshlrev_b32_e32 v112, 16, v116
	s_waitcnt lgkmcnt(4)
	v_lshlrev_b32_e32 v113, 16, v117
	v_add_f32_dpp v73, v73, v73 quad_perm:[1,0,3,2] row_mask:0xf bank_mask:0xf bound_ctrl:1
	s_waitcnt lgkmcnt(2)
	v_lshlrev_b32_e32 v110, 16, v140
	v_add_f32_e32 v95, 0, v108
	v_add_f32_dpp v73, v73, v73 quad_perm:[2,3,0,1] row_mask:0xf bank_mask:0xf bound_ctrl:1
	v_lshlrev_b32_e32 v109, 16, v114
	v_add_f32_e32 v95, v95, v110
	v_add_f32_dpp v73, v73, v73 row_half_mirror row_mask:0xf bank_mask:0xf bound_ctrl:1
	v_mul_f32_e32 v116, 0x3c800000, v73
	v_pk_add_f32 v[100:101], v[100:101], v[116:117] op_sel_hi:[1,0] neg_lo:[0,1] neg_hi:[0,1]
	v_pk_add_f32 v[102:103], v[102:103], v[116:117] op_sel_hi:[1,0] neg_lo:[0,1] neg_hi:[0,1]
	v_pk_add_f32 v[104:105], v[104:105], v[116:117] op_sel_hi:[1,0] neg_lo:[0,1] neg_hi:[0,1]
	v_pk_add_f32 v[106:107], v[106:107], v[116:117] op_sel_hi:[1,0] neg_lo:[0,1] neg_hi:[0,1]
	v_mov_b32_e32 v116, v103
	v_mov_b32_e32 v117, v101
	v_mul_f32_e32 v73, v100, v100
	v_pk_mul_f32 v[116:117], v[116:117], v[116:117]
	v_fmac_f32_e32 v73, v102, v102
	v_mov_b32_e32 v142, v106
	v_mov_b32_e32 v143, v104
	v_add_f32_e32 v73, v117, v73
	v_pk_mul_f32 v[142:143], v[142:143], v[142:143]
	v_add_f32_e32 v73, v116, v73
	v_mov_b32_e32 v144, v107
	v_mov_b32_e32 v145, v105
	v_add_f32_e32 v73, v143, v73
	v_pk_mul_f32 v[144:145], v[144:145], v[144:145]
	v_add_f32_e32 v73, v142, v73
	v_add_f32_e32 v73, v145, v73
	v_add_f32_e32 v73, v144, v73
	v_lshlrev_b32_e32 v111, 16, v115
	v_add_f32_e32 v95, v95, v109
	v_add_f32_dpp v73, v73, v73 quad_perm:[1,0,3,2] row_mask:0xf bank_mask:0xf bound_ctrl:1
	v_add_f32_e32 v95, v95, v111
	v_lshlrev_b32_e32 v114, 16, v133
	v_add_f32_dpp v73, v73, v73 quad_perm:[2,3,0,1] row_mask:0xf bank_mask:0xf bound_ctrl:1
	v_add_f32_e32 v95, v95, v112
	v_add_f32_e32 v95, v95, v114
	v_add_f32_dpp v73, v73, v73 row_half_mirror row_mask:0xf bank_mask:0xf bound_ctrl:1
	v_fmamk_f32 v73, v73, 0x3c800000, v184
	v_rsq_f32_e32 v116, v73
	s_waitcnt lgkmcnt(1)
	v_lshlrev_b32_e32 v115, 16, v141
	v_add_f32_e32 v95, v95, v113
	v_add_f32_e32 v95, v95, v115
	v_pk_mul_f32 v[100:101], v[100:101], v[116:117] op_sel_hi:[1,0]
	v_pk_mul_f32 v[102:103], v[102:103], v[116:117] op_sel_hi:[1,0]
	v_add_f32_dpp v95, v95, v95 quad_perm:[1,0,3,2] row_mask:0xf bank_mask:0xf bound_ctrl:1
	v_pk_mul_f32 v[104:105], v[104:105], v[116:117] op_sel_hi:[1,0]
	v_pk_mul_f32 v[106:107], v[106:107], v[116:117] op_sel_hi:[1,0]
	v_add_f32_dpp v95, v95, v95 quad_perm:[2,3,0,1] row_mask:0xf bank_mask:0xf bound_ctrl:1
	v_pk_fma_f32 v[100:101], v[66:67], v[100:101], v[62:63]
	v_pk_fma_f32 v[102:103], v[80:81], v[102:103], v[78:79]
	v_add_f32_dpp v95, v95, v95 row_half_mirror row_mask:0xf bank_mask:0xf bound_ctrl:1
	v_pk_fma_f32 v[104:105], v[70:71], v[104:105], v[74:75]
	v_pk_fma_f32 v[106:107], v[68:69], v[106:107], v[64:65]
	v_mul_f32_e32 v140, 0x3c800000, v95
	v_add_u32_e32 v83, 0x80, v83
	v_lshlrev_b32_e32 v117, 16, v85
	v_lshlrev_b32_e32 v116, 16, v84
	v_and_b32_e32 v85, 0xffff0000, v85
	v_and_b32_e32 v84, 0xffff0000, v84
	v_lshlrev_b32_e32 v145, 16, v89
	v_lshlrev_b32_e32 v144, 16, v88
	v_and_b32_e32 v89, 0xffff0000, v89
	v_and_b32_e32 v88, 0xffff0000, v88
	v_lshlrev_b32_e32 v147, 16, v91
	v_lshlrev_b32_e32 v146, 16, v90
	v_and_b32_e32 v91, 0xffff0000, v91
	v_and_b32_e32 v90, 0xffff0000, v90
	v_lshlrev_b32_e32 v143, 16, v87
	v_lshlrev_b32_e32 v142, 16, v86
	v_and_b32_e32 v87, 0xffff0000, v87
	v_and_b32_e32 v86, 0xffff0000, v86
	v_pk_fma_f32 v[100:101], v[94:95], v[144:145], v[100:101] op_sel_hi:[0,1,1]
	v_pk_fma_f32 v[88:89], v[94:95], v[88:89], v[102:103] op_sel_hi:[0,1,1]
	v_pk_fma_f32 v[102:103], v[94:95], v[146:147], v[104:105] op_sel_hi:[0,1,1]
	v_pk_fma_f32 v[90:91], v[94:95], v[90:91], v[106:107] op_sel_hi:[0,1,1]
	v_pk_mul_f32 v[94:95], v[100:101], v[116:117]
	v_pk_mul_f32 v[84:85], v[88:89], v[84:85]
	v_pk_mul_f32 v[88:89], v[102:103], v[142:143]
	v_pk_mul_f32 v[86:87], v[90:91], v[86:87]
	v_bfe_u32 v101, v94, 16, 1
	v_bfe_u32 v73, v87, 16, 1
	v_bfe_u32 v90, v86, 16, 1
	v_bfe_u32 v102, v95, 16, 1
	v_bfe_u32 v103, v88, 16, 1
	v_bfe_u32 v104, v89, 16, 1
	v_bfe_u32 v91, v85, 16, 1
	v_bfe_u32 v100, v84, 16, 1
	v_add3_u32 v86, v86, v90, s33
	v_add3_u32 v73, v87, v73, s33
	v_add3_u32 v87, v89, v104, s33
	v_add3_u32 v88, v88, v103, s33
	v_add3_u32 v89, v95, v102, s33
	v_add3_u32 v90, v94, v101, s33
	v_add3_u32 v84, v84, v100, s33
	v_add3_u32 v85, v85, v91, s33
	v_lshrrev_b32_e32 v90, 16, v90
	v_lshrrev_b32_e32 v89, 16, v89
	v_lshrrev_b32_e32 v88, 16, v88
	v_lshrrev_b32_e32 v87, 16, v87
	v_and_or_b32 v87, v73, s1, v87
	v_and_or_b32 v86, v86, s1, v88
	v_and_or_b32 v85, v85, s1, v89
	v_and_or_b32 v84, v84, s1, v90
	global_store_dwordx4 v[92:93], v[84:87], off
	s_waitcnt vmcnt(4)
	s_nop 1
	v_mov_b32_e32 v84, v216
	v_mov_b32_e32 v85, v217
	v_mov_b32_e32 v86, v218
	v_mov_b32_e32 v87, v219
	s_nop 0
	s_waitcnt vmcnt(3)
	s_nop 1
	v_mov_b32_e32 v88, v220
	v_mov_b32_e32 v89, v221
	v_mov_b32_e32 v90, v222
	v_mov_b32_e32 v91, v223
	v_pk_add_f32 v[92:93], v[108:109], v[140:141] op_sel_hi:[1,0] neg_lo:[0,1] neg_hi:[0,1]
	v_pk_add_f32 v[94:95], v[110:111], v[140:141] op_sel_hi:[1,0] neg_lo:[0,1] neg_hi:[0,1]
	v_mov_b32_e32 v101, v93
	v_mov_b32_e32 v100, v95
	v_mul_f32_e32 v73, v92, v92
	v_pk_add_f32 v[96:97], v[112:113], v[140:141] op_sel_hi:[1,0] neg_lo:[0,1] neg_hi:[0,1]
	v_pk_add_f32 v[98:99], v[114:115], v[140:141] op_sel_hi:[1,0] neg_lo:[0,1] neg_hi:[0,1]
	v_pk_mul_f32 v[100:101], v[100:101], v[100:101]
	v_fmac_f32_e32 v73, v94, v94
	v_mov_b32_e32 v102, v98
	v_mov_b32_e32 v103, v96
	v_add_f32_e32 v73, v101, v73
	v_pk_mul_f32 v[102:103], v[102:103], v[102:103]
	v_add_f32_e32 v73, v100, v73
	v_mov_b32_e32 v104, v99
	v_mov_b32_e32 v105, v97
	v_add_f32_e32 v73, v103, v73
	v_pk_mul_f32 v[104:105], v[104:105], v[104:105]
	v_add_f32_e32 v73, v102, v73
	v_add_f32_e32 v73, v105, v73
	v_add_f32_e32 v73, v104, v73
	s_add_u32 s68, s68, 0x40000
	s_addc_u32 s69, s69, 0
	v_add_f32_dpp v73, v73, v73 quad_perm:[1,0,3,2] row_mask:0xf bank_mask:0xf bound_ctrl:1
	v_add_u32_e32 v5, 0x100, v5
	v_add_u32_e32 v72, 64, v72
	v_add_f32_dpp v73, v73, v73 quad_perm:[2,3,0,1] row_mask:0xf bank_mask:0xf bound_ctrl:1
	s_cmp_lg_u32 s68, 0x80000
	v_lshlrev_b32_e32 v105, 16, v87
	v_add_f32_dpp v73, v73, v73 row_half_mirror row_mask:0xf bank_mask:0xf bound_ctrl:1
	v_fmamk_f32 v73, v73, 0x3c800000, v184
	v_rsq_f32_e32 v100, v73
	v_lshlrev_b32_e32 v104, 16, v86
	v_and_b32_e32 v87, 0xffff0000, v87
	v_and_b32_e32 v86, 0xffff0000, v86
	v_pk_mul_f32 v[92:93], v[92:93], v[100:101] op_sel_hi:[1,0]
	v_pk_mul_f32 v[94:95], v[94:95], v[100:101] op_sel_hi:[1,0]
	v_pk_mul_f32 v[96:97], v[96:97], v[100:101] op_sel_hi:[1,0]
	v_pk_mul_f32 v[98:99], v[98:99], v[100:101] op_sel_hi:[1,0]
	v_pk_fma_f32 v[92:93], v[66:67], v[92:93], v[62:63]
	v_pk_fma_f32 v[94:95], v[80:81], v[94:95], v[78:79]
	v_pk_fma_f32 v[96:97], v[70:71], v[96:97], v[74:75]
	v_pk_fma_f32 v[98:99], v[68:69], v[98:99], v[64:65]
	v_lshlrev_b32_e32 v101, 16, v85
	v_lshlrev_b32_e32 v100, 16, v84
	v_and_b32_e32 v85, 0xffff0000, v85
	v_and_b32_e32 v84, 0xffff0000, v84
	v_lshlrev_b32_e32 v103, 16, v89
	v_lshlrev_b32_e32 v102, 16, v88
	v_and_b32_e32 v89, 0xffff0000, v89
	v_and_b32_e32 v88, 0xffff0000, v88
	v_lshlrev_b32_e32 v107, 16, v91
	v_lshlrev_b32_e32 v106, 16, v90
	v_and_b32_e32 v91, 0xffff0000, v91
	v_and_b32_e32 v90, 0xffff0000, v90
	s_waitcnt lgkmcnt(0)
	v_pk_fma_f32 v[92:93], v[82:83], v[100:101], v[92:93] op_sel_hi:[0,1,1]
	v_pk_fma_f32 v[84:85], v[82:83], v[84:85], v[94:95] op_sel_hi:[0,1,1]
	v_pk_fma_f32 v[94:95], v[82:83], v[104:105], v[96:97] op_sel_hi:[0,1,1]
	v_pk_fma_f32 v[86:87], v[82:83], v[86:87], v[98:99] op_sel_hi:[0,1,1]
	v_pk_mul_f32 v[92:93], v[92:93], v[102:103]
	v_pk_mul_f32 v[84:85], v[84:85], v[88:89]
	v_pk_mul_f32 v[88:89], v[94:95], v[106:107]
	v_pk_mul_f32 v[86:87], v[86:87], v[90:91]
	v_bfe_u32 v94, v92, 16, 1
	v_bfe_u32 v73, v87, 16, 1
	v_bfe_u32 v82, v86, 16, 1
	v_bfe_u32 v95, v93, 16, 1
	v_bfe_u32 v96, v88, 16, 1
	v_bfe_u32 v97, v89, 16, 1
	v_bfe_u32 v90, v85, 16, 1
	v_bfe_u32 v91, v84, 16, 1
	v_add3_u32 v82, v86, v82, s33
	v_add3_u32 v73, v87, v73, s33
	v_add3_u32 v86, v89, v97, s33
	v_add3_u32 v87, v88, v96, s33
	v_add3_u32 v88, v93, v95, s33
	v_add3_u32 v89, v92, v94, s33
	v_add3_u32 v84, v84, v91, s33
	v_add3_u32 v85, v85, v90, s33
	v_lshrrev_b32_e32 v89, 16, v89
	v_lshrrev_b32_e32 v88, 16, v88
	v_lshrrev_b32_e32 v90, 16, v87
	v_lshrrev_b32_e32 v86, 16, v86
	v_and_or_b32 v87, v73, s1, v86
	v_and_or_b32 v86, v82, s1, v90
	v_and_or_b32 v85, v85, s1, v88
	v_and_or_b32 v84, v84, s1, v89
	global_store_dwordx4 v[76:77], v[84:87], off
